# attention loops: 1+e for register pairs via one v_pk_add_f32, reciprocals in place (9 pairs)
# baseline (speedup 1.0000x reference)
; __device__ __forceinline__ void attn_phase(const bf16_t* Q, const bf16_t* KF, const bf16_t* V, bf16_t* VT, bf16_t* O, LAS unsigned char* lds, unsigned* ctr) {
;     ...
;             unsigned uq = 0u;
;             if (lane == 0) uq = atomicAdd(ctr, 1u);
;             uq = (unsigned)__builtin_amdgcn_readfirstlane((int)uq);
;             if (uq >= 64u) break;
;             const int qb = 63 - (int)uq, t0 = qb * 32;
;             bf16x8 qf[4];
; #pragma unroll
;             for (int kd = 0; kd < 4; ++kd) qf[kd] = *(const bf16x8*)(Q + (size_t)(b * 16 + h) * 64 * SEQ + (size_t)((qb * 4 + kd) * 64 + lane) * 8);
;             f32x16 o0 = {0.f, 0.f, 0.f, 0.f, 0.f, 0.f, 0.f, 0.f, 0.f, 0.f, 0.f, 0.f, 0.f, 0.f, 0.f, 0.f}, o1 = o0;
;             float Pc = 1.0f;
;             bf16x8 kfn[4];
; #pragma unroll
;             for (int kd = 0; kd < 4; ++kd) kfn[kd] = *(const bf16x8*)(kfw + (size_t)((qb * 4 + kd) * 64 + lane) * 8);
;     ...
;                 f32x16 z = {0.f, 0.f, 0.f, 0.f, 0.f, 0.f, 0.f, 0.f, 0.f, 0.f, 0.f, 0.f, 0.f, 0.f, 0.f, 0.f};
; #pragma unroll
;                 for (int kd = 0; kd < 4; ++kd) z = __builtin_amdgcn_mfma_f32_32x32x16_bf16(kfn[kd], qf[kd], z, 0, 0, 0);
;                 { const int ktn = kt > 0 ? kt - 1 : kt;
; #pragma unroll
;                   for (int kd = 0; kd < 4; ++kd) kfn[kd] = *(const bf16x8*)(kfw + (size_t)((ktn * 4 + kd) * 64 + lane) * 8); }
;                 bf16x8 vf[2][2];
; #pragma unroll
;                 for (int db = 0; db < 2; ++db)
; #pragma unroll
;                     for (int ks = 0; ks < 2; ++ks) vf[db][ks] = *(const bf16x8*)(vtb + (size_t)((((kt * 2 + db) * 2 + ks) * 64) + lane) * 8);
;                 float be[16], om[16];
; #pragma unroll
;                 for (int r = 0; r < 16; ++r) { const float e = __builtin_amdgcn_exp2f(-fmaxf(z[r], -80.0f)); be[r] = __builtin_amdgcn_rcpf(1.0f + e); om[r] = e * be[r]; }
;                 if (kt == qb) {
; #pragma unroll
;                     for (int r = 0; r < 16; ++r) { const int sl = 8 * (r >> 2) + 4 * hf + (r & 3); const bool valid = sl < c32; be[r] = valid ? be[r] : 0.f; om[r] = valid ? om[r] : 1.0f; } }
;                 float bp[4], pbp[4];
; #pragma unroll
;                 for (int q = 0; q < 4; ++q) { bp[q] = (om[4 * q] * om[4 * q + 1]) * (om[4 * q + 2] * om[4 * q + 3]); pbp[q] = __shfl_xor(bp[q], 32); }
;                 float after = Pc; float att[16];
; #pragma unroll
.LBB0_1749:
	s_or_b64 exec, exec, s[86:87]
	v_readfirstlane_b32 s79, v0
	s_cmp_gt_u32 s79, 63
	s_mov_b64 s[86:87], -1
	s_cbranch_scc1 .LBB0_1744
	s_sub_i32 s9, 63, s79
	s_lshl_b32 s63, s9, 12
	v_lshl_or_b32 v28, v85, 1, s63
	global_load_dwordx4 v[0:3], v28, s[82:83]
	global_load_dwordx4 v[48:51], v28, s[84:85]
	global_load_dwordx4 v[16:19], v28, s[82:83] offset:1024
	global_load_dwordx4 v[52:55], v28, s[84:85] offset:1024
	global_load_dwordx4 v[20:23], v28, s[82:83] offset:2048
	global_load_dwordx4 v[56:59], v28, s[84:85] offset:2048
	global_load_dwordx4 v[24:27], v28, s[82:83] offset:3072
	global_load_dwordx4 v[60:63], v28, s[84:85] offset:3072
	v_or_b32_e32 v28, s63, v86
	s_waitcnt vmcnt(6)
	v_mfma_f32_32x32x16_bf16 v[0:15], v[0:3], v[48:51], 0
	s_waitcnt vmcnt(4)
	v_mfma_f32_32x32x16_bf16 v[0:15], v[16:19], v[52:55], v[0:15]
	v_and_b32_e32 v17, 64, v102
	v_xor_b32_e32 v16, 32, v102
	v_add_u32_e32 v17, 64, v17
	v_cmp_lt_i32_e32 vcc, v16, v17
	s_nop 1
	v_cndmask_b32_e32 v16, v102, v16, vcc
	s_waitcnt vmcnt(2)
	v_mfma_f32_32x32x16_bf16 v[0:15], v[20:23], v[56:59], v[0:15]
	v_lshlrev_b32_e32 v104, 2, v16
	global_load_dwordx4 v[20:23], v28, s[80:81]
	global_load_dwordx4 v[32:35], v28, s[80:81] offset:1024
	global_load_dwordx4 v[16:19], v28, s[80:81] offset:2048
	global_load_dwordx4 v[36:39], v28, s[80:81] offset:3072
	s_waitcnt vmcnt(4)
	v_mfma_f32_32x32x16_bf16 v[0:15], v[24:27], v[60:63], v[0:15]
	s_nop 11
	v_min_f32_e64 v1, -v1, s98
	v_min_f32_e64 v4, -v4, s98
	v_min_f32_e64 v5, -v5, s98
	v_min_f32_e64 v6, -v6, s98
	v_min_f32_e64 v7, -v7, s98
	v_min_f32_e64 v0, -v0, s98
	v_min_f32_e64 v2, -v2, s98
	v_min_f32_e64 v3, -v3, s98
	v_exp_f32_e32 v25, v1
	v_exp_f32_e32 v28, v4
	v_exp_f32_e32 v29, v5
	v_exp_f32_e32 v30, v6
	v_exp_f32_e32 v31, v7
	v_exp_f32_e32 v24, v0
	v_exp_f32_e32 v26, v2
	v_exp_f32_e32 v27, v3
	v_min_f32_e64 v9, -v9, s98
	v_min_f32_e64 v12, -v12, s98
	v_min_f32_e64 v13, -v13, s98
	v_min_f32_e64 v14, -v14, s98
	v_min_f32_e64 v15, -v15, s98
	v_min_f32_e64 v8, -v8, s98
	v_min_f32_e64 v10, -v10, s98
	v_min_f32_e64 v11, -v11, s98
	v_exp_f32_e32 v3, v9
	v_exp_f32_e32 v0, v12
	v_exp_f32_e32 v2, v13
	v_exp_f32_e32 v4, v14
	v_exp_f32_e32 v6, v15
	v_add_f32_e32 v9, 1.0, v25
	v_add_f32_e32 v12, 1.0, v28
	v_add_f32_e32 v13, 1.0, v29
	v_add_f32_e32 v14, 1.0, v30
	v_add_f32_e32 v15, 1.0, v31
	v_exp_f32_e32 v1, v8
	v_exp_f32_e32 v5, v10
	v_exp_f32_e32 v7, v11
	v_add_f32_e32 v8, 1.0, v24
	v_pk_add_f32 v[72:73], v[26:27], 1.0 op_sel_hi:[1,0]
	v_rcp_f32_e32 v64, v9
	v_rcp_f32_e32 v12, v12
	v_rcp_f32_e32 v74, v13
	v_rcp_f32_e32 v14, v14
	v_rcp_f32_e32 v75, v15
	v_rcp_f32_e32 v47, v8
	v_rcp_f32_e32 v72, v72
	v_rcp_f32_e32 v73, v73
	v_mul_f32_e32 v25, v25, v64
	v_mul_f32_e32 v28, v28, v12
	v_mul_f32_e32 v29, v29, v74
	v_mul_f32_e32 v30, v30, v14
	v_mul_f32_e32 v31, v31, v75
	v_mul_f32_e32 v24, v24, v47
	v_mul_f32_e32 v26, v26, v72
	v_mul_f32_e32 v27, v27, v73
	v_cndmask_b32_e64 v80, 0, v14, s[28:29]
	v_cndmask_b32_e64 v81, 1.0, v25, s[18:19]
	v_cndmask_b32_e64 v14, 1.0, v28, s[24:25]
	v_cndmask_b32_e64 v25, 1.0, v29, s[26:27]
	v_cndmask_b32_e64 v29, 1.0, v30, s[28:29]
	v_cndmask_b32_e64 v105, 1.0, v31, s[30:31]
	v_cndmask_b32_e64 v79, 0, v12, s[24:25]
	v_cndmask_b32_e64 v12, 1.0, v24, s[16:17]
	v_cndmask_b32_e64 v82, 1.0, v26, s[20:21]
	v_cndmask_b32_e64 v83, 1.0, v27, s[22:23]
	v_mul_f32_e32 v14, v14, v25
	v_mul_f32_e32 v26, v29, v105
	v_add_f32_e32 v42, 1.0, v5
	v_add_f32_e32 v43, 1.0, v7
	v_pk_add_f32 v[8:9], v[0:1], 1.0 op_sel_hi:[1,0]
	v_pk_add_f32 v[10:11], v[2:3], 1.0 op_sel_hi:[1,0]
	v_add_f32_e32 v46, 1.0, v4
	v_mul_f32_e32 v12, v12, v81
	v_mul_f32_e32 v24, v82, v83
	v_mul_f32_e32 v26, v14, v26
	v_add_f32_e32 v14, 1.0, v6
	v_rcp_f32_e32 v13, v42
	v_rcp_f32_e32 v15, v43
	v_rcp_f32_e32 v8, v8
	v_rcp_f32_e32 v9, v9
	v_rcp_f32_e32 v10, v10
	v_rcp_f32_e32 v11, v11
	v_mul_f32_e32 v24, v12, v24
	v_rcp_f32_e32 v12, v46
	v_rcp_f32_e32 v14, v14
	v_pk_mul_f32 v[0:1], v[0:1], v[8:9]
	v_pk_mul_f32 v[2:3], v[2:3], v[10:11]
	v_pk_mul_f32 v[4:5], v[4:5], v[12:13]
	v_pk_mul_f32 v[6:7], v[6:7], v[14:15]
	v_cndmask_b32_e64 v1, 1.0, v1, s[34:35]
	v_cndmask_b32_e64 v0, 1.0, v0, s[36:37]
	v_cndmask_b32_e64 v41, 1.0, v3, s[38:39]
	v_cndmask_b32_e64 v40, 1.0, v2, s[40:41]
	v_cndmask_b32_e64 v43, 1.0, v5, s[42:43]
	v_cndmask_b32_e64 v42, 1.0, v4, s[44:45]
	v_cndmask_b32_e64 v45, 1.0, v7, s[46:47]
	v_cndmask_b32_e64 v44, 1.0, v6, s[48:49]
	v_pk_mul_f32 v[0:1], v[0:1], v[40:41]
	v_pk_mul_f32 v[2:3], v[42:43], v[44:45]
	v_cndmask_b32_e64 v76, 0, v47, s[16:17]
	v_pk_mul_f32 v[0:1], v[0:1], v[2:3]
	ds_bpermute_b32 v46, v104, v0
	ds_bpermute_b32 v47, v104, v1
	ds_bpermute_b32 v30, v104, v26
	v_cndmask_b32_e64 v77, 0, v72, s[20:21]
	v_cndmask_b32_e64 v78, 0, v73, s[22:23]
	s_waitcnt lgkmcnt(2)
	v_cndmask_b32_e64 v5, 1.0, v46, s[14:15]
	s_waitcnt lgkmcnt(1)
	v_pk_mul_f32 v[72:73], v[0:1], v[46:47]
	v_mul_f32_e32 v6, v5, v44
	v_mov_b32_e32 v27, v72
	v_mov_b32_e32 v31, v73
	v_cndmask_b32_e64 v2, 0, v10, s[40:41]
	v_mul_f32_e32 v7, v42, v6
	s_waitcnt lgkmcnt(0)
	v_pk_mul_f32 v[0:1], v[26:27], v[30:31]
	ds_bpermute_b32 v28, v104, v24
	v_mul_f32_e32 v42, v2, v7
	v_mul_f32_e32 v2, v1, v30
	v_cndmask_b32_e64 v3, 0, v12, s[44:45]
	v_cndmask_b32_e64 v2, v1, v2, s[14:15]
	v_cndmask_b32_e64 v4, 0, v14, s[48:49]
	v_mul_f32_e32 v111, v3, v6
	v_mul_f32_e32 v3, v105, v2
	v_mul_f32_e32 v44, v5, v4
	v_mul_f32_e32 v4, v29, v3
	v_cndmask_b32_e64 v74, 0, v74, s[26:27]
	v_cndmask_b32_e64 v75, 0, v75, s[30:31]
	v_mul_f32_e32 v5, v25, v4
	v_mov_b32_e32 v25, v0
	v_mov_b32_e32 v29, v1
	v_mul_f32_e32 v2, v75, v2
	v_mul_f32_e32 v4, v74, v4
	s_waitcnt lgkmcnt(0)
; __device__ __forceinline__ void attn_phase(const bf16_t* Q, const bf16_t* KF, const bf16_t* V, bf16_t* VT, bf16_t* O, LAS unsigned char* lds, unsigned* ctr) {
;     ...
;                 float after = Pc; float att[16];
; #pragma unroll
;                 for (int q = 3; q >= 0; --q) {
;                     const float off = hf == 0 ? after * pbp[q] : after;
;                     const float e3 = off, e2 = e3 * om[4 * q + 3], e1 = e2 * om[4 * q + 2], e0 = e1 * om[4 * q + 1];
;                     att[4 * q + 3] = be[4 * q + 3] * e3; att[4 * q + 2] = be[4 * q + 2] * e2; att[4 * q + 1] = be[4 * q + 1] * e1; att[4 * q] = be[4 * q] * e0;
;                     after *= bp[q] * pbp[q];
;                 }
;                 Pc = after;
; #pragma unroll
;                 for (int ks = 0; ks < 2; ++ks) {
;                     const bf16x8 pf = __builtin_bit_cast(bf16x8, (u32x4){cvt_pk_bf16(att[8 * ks], att[8 * ks + 1]), cvt_pk_bf16(att[8 * ks + 2], att[8 * ks + 3]), cvt_pk_bf16(att[8 * ks + 4], att[8 * ks + 5]), cvt_pk_bf16(att[8 * ks + 6], att[8 * ks + 7])});
;                     o0 = __builtin_amdgcn_mfma_f32_32x32x16_bf16(vf[0][ks], pf, o0, 0, 0, 0); o1 = __builtin_amdgcn_mfma_f32_32x32x16_bf16(vf[1][ks], pf, o1, 0, 0, 0); }
;                 if (__all(Pc == 0.0f)) break;
	v_pk_mul_f32 v[74:75], v[24:25], v[28:29]
	v_cndmask_b32_e64 v64, 0, v64, s[18:19]
	v_mul_f32_e32 v0, v75, v28
	v_cndmask_b32_e64 v0, v75, v0, s[14:15]
	v_mul_f32_e32 v1, v83, v0
	v_mul_f32_e32 v6, v82, v1
	v_mul_f32_e32 v40, v40, v7
	v_mul_f32_e32 v7, v81, v6
	v_mul_f32_e32 v3, v80, v3
	v_mul_f32_e32 v5, v79, v5
	v_mul_f32_e32 v0, v78, v0
	v_mul_f32_e32 v1, v77, v1
	v_mul_f32_e32 v6, v64, v6
	v_mul_f32_e32 v7, v76, v7
	v_cvt_pk_bf16_f32 v24, v7, v6
	v_cvt_pk_bf16_f32 v25, v1, v0
	v_cvt_pk_bf16_f32 v26, v5, v4
	v_cvt_pk_bf16_f32 v27, v3, v2
	v_cndmask_b32_e64 v106, 0, v9, s[34:35]
	v_cndmask_b32_e64 v107, 0, v11, s[38:39]
	v_cndmask_b32_e64 v108, 0, v13, s[42:43]
	v_cndmask_b32_e64 v109, 0, v15, s[46:47]
	v_cndmask_b32_e64 v110, 0, v8, s[36:37]
	s_waitcnt vmcnt(3)
	v_mfma_f32_32x32x16_bf16 v[0:15], v[20:23], v[24:27], 0
	v_mul_f32_e32 v20, v72, v47
	v_cndmask_b32_e64 v20, v72, v20, s[14:15]
	v_mul_f32_e32 v46, v110, v40
	v_mul_f32_e32 v40, v45, v20
	v_mul_f32_e32 v45, v109, v20
	v_mul_f32_e32 v43, v43, v40
	v_mul_f32_e32 v41, v41, v43
	s_waitcnt vmcnt(1)
	v_mfma_f32_32x32x16_bf16 v[16:31], v[16:19], v[24:27], 0
	v_mul_f32_e32 v47, v108, v40
	v_mul_f32_e32 v40, v107, v43
	v_mul_f32_e32 v41, v106, v41
	v_cvt_pk_bf16_f32 v40, v41, v40
	v_cvt_pk_bf16_f32 v41, v47, v45
	v_cvt_pk_bf16_f32 v42, v46, v42
	v_cvt_pk_bf16_f32 v43, v111, v44
	v_mul_f32_e32 v77, v74, v75
	v_cmp_eq_f32_e32 vcc, 0, v77
	v_mfma_f32_32x32x16_bf16 v[0:15], v[32:35], v[40:43], v[0:15]
	s_cmp_eq_u64 vcc, exec
	s_cselect_b64 s[86:87], -1, 0
	s_cmp_eq_u32 s79, 63
	s_cselect_b64 s[88:89], -1, 0
	s_or_b64 s[86:87], s[88:89], s[86:87]
	s_and_b64 vcc, exec, s[86:87]
	s_waitcnt vmcnt(0)
	v_mfma_f32_32x32x16_bf16 v[16:31], v[36:39], v[40:43], v[16:31]
	s_cbranch_vccnz .LBB0_1743
	s_lshl_b32 s63, s79, 12
	v_subrev_u32_e32 v32, s63, v86
	v_add_u32_e32 v64, 0x3e000, v32
	v_lshl_add_u64 v[32:33], s[82:83], 0, v[64:65]
	s_mov_b64 s[86:87], 0xc00
	s_sub_i32 s63, 62, s79
	s_sub_i32 s72, s79, 62
	s_lshl_b32 s79, s79, 8
	v_lshl_add_u64 v[78:79], v[32:33], 0, s[86:87]
	v_lshl_add_u64 v[80:81], v[32:33], 0, s[74:75]
	v_lshl_add_u64 v[74:75], v[32:33], 0, s[76:77]
	v_subrev_u32_e32 v72, s79, v89
	v_mov_b64_e32 v[82:83], v[64:65]
; __device__ __forceinline__ void attn_phase(const bf16_t* Q, const bf16_t* KF, const bf16_t* V, bf16_t* VT, bf16_t* O, LAS unsigned char* lds, unsigned* ctr) {
;     ...
;                 f32x16 z = {0.f, 0.f, 0.f, 0.f, 0.f, 0.f, 0.f, 0.f, 0.f, 0.f, 0.f, 0.f, 0.f, 0.f, 0.f, 0.f};
; #pragma unroll
;                 for (int kd = 0; kd < 4; ++kd) z = __builtin_amdgcn_mfma_f32_32x32x16_bf16(kfn[kd], qf[kd], z, 0, 0, 0);
;                 { const int ktn = kt > 0 ? kt - 1 : kt;
; #pragma unroll
;                   for (int kd = 0; kd < 4; ++kd) kfn[kd] = *(const bf16x8*)(kfw + (size_t)((ktn * 4 + kd) * 64 + lane) * 8); }
;                 bf16x8 vf[2][2];
; #pragma unroll
;                 for (int db = 0; db < 2; ++db)
; #pragma unroll
;                     for (int ks = 0; ks < 2; ++ks) vf[db][ks] = *(const bf16x8*)(vtb + (size_t)((((kt * 2 + db) * 2 + ks) * 64) + lane) * 8);
;                 float be[16], om[16];
; #pragma unroll
;                 for (int r = 0; r < 16; ++r) { const float e = __builtin_amdgcn_exp2f(-fmaxf(z[r], -80.0f)); be[r] = __builtin_amdgcn_rcpf(1.0f + e); om[r] = e * be[r]; }
;                 if (kt == qb) {
; #pragma unroll
;                     for (int r = 0; r < 16; ++r) { const int sl = 8 * (r >> 2) + 4 * hf + (r & 3); const bool valid = sl < c32; be[r] = valid ? be[r] : 0.f; om[r] = valid ? om[r] : 1.0f; } }
;                 float bp[4], pbp[4];
; #pragma unroll
;                 for (int q = 0; q < 4; ++q) { bp[q] = (om[4 * q] * om[4 * q + 1]) * (om[4 * q + 2] * om[4 * q + 3]); pbp[q] = __shfl_xor(bp[q], 32); }
;                 float after = Pc; float att[16];
; #pragma unroll
;                 for (int q = 3; q >= 0; --q) {
;                     const float off = hf == 0 ? after * pbp[q] : after;
;                     const float e3 = off, e2 = e3 * om[4 * q + 3], e1 = e2 * om[4 * q + 2], e0 = e1 * om[4 * q + 1];
;                     att[4 * q + 3] = be[4 * q + 3] * e3; att[4 * q + 2] = be[4 * q + 2] * e2; att[4 * q + 1] = be[4 * q + 1] * e1; att[4 * q] = be[4 * q] * e0;
;                     after *= bp[q] * pbp[q];
;                 }
;                 Pc = after;
; #pragma unroll
;                 for (int ks = 0; ks < 2; ++ks) {
.LBB0_1752:
	v_lshl_add_u64 v[32:33], s[82:83], 0, v[82:83]
	global_load_dwordx4 v[32:35], v[32:33], off
	s_nop 0
	global_load_dwordx4 v[106:109], v[74:75], off
	global_load_dwordx4 v[110:113], v[80:81], off
	global_load_dwordx4 v[114:117], v[78:79], off
	s_min_u32 s79, s63, 1
	s_lshl_b32 s79, s79, 8
	v_subrev_u32_e32 v36, s79, v72
	v_add_u32_e32 v38, 0xffffff40, v36
	v_ashrrev_i32_e32 v39, 31, v38
	v_lshlrev_b64 v[82:83], 4, v[38:39]
	v_add_u32_e32 v38, 0xffffff80, v36
	v_ashrrev_i32_e32 v39, 31, v38
	v_lshl_add_u64 v[74:75], v[38:39], 4, s[82:83]
	v_subrev_u32_e32 v38, 64, v36
	v_ashrrev_i32_e32 v39, 31, v38
	v_ashrrev_i32_e32 v37, 31, v36
	v_lshl_add_u64 v[80:81], v[38:39], 4, s[82:83]
	v_lshl_add_u64 v[78:79], v[36:37], 4, s[82:83]
	v_add_u32_e32 v64, 0xffffff40, v72
	v_mov_b32_e32 v73, v65
	v_lshl_add_u64 v[122:123], v[72:73], 4, s[80:81]
	s_waitcnt vmcnt(3)
	v_mfma_f32_32x32x16_bf16 v[32:47], v[32:35], v[48:51], 0
	global_load_dwordx4 v[122:125], v[122:123], off
	s_waitcnt vmcnt(3)
	v_mfma_f32_32x32x16_bf16 v[32:47], v[106:109], v[52:55], v[32:47]
	v_lshl_add_u64 v[106:107], v[64:65], 4, s[80:81]
	v_add_u32_e32 v64, 0xffffff80, v72
	global_load_dwordx4 v[106:109], v[106:107], off
	s_waitcnt vmcnt(3)
	v_mfma_f32_32x32x16_bf16 v[32:47], v[110:113], v[56:59], v[32:47]
	v_lshl_add_u64 v[110:111], v[64:65], 4, s[80:81]
	v_subrev_u32_e32 v64, 64, v72
	v_lshl_add_u64 v[118:119], v[64:65], 4, s[80:81]
	global_load_dwordx4 v[118:121], v[118:119], off
	v_add_u32_e32 v72, 0xffffff00, v72
	global_load_dwordx4 v[110:113], v[110:111], off
	s_waitcnt vmcnt(4)
	v_mfma_f32_32x32x16_bf16 v[32:47], v[114:117], v[60:63], v[32:47]
	s_nop 11
	v_min_f32_e64 v33, -v33, s98
	v_exp_f32_e32 v114, v33
	v_max_f32_e64 v33, -v34, -v34
	v_min_f32_e64 v34, -v35, s98
	v_exp_f32_e32 v115, v34
	v_min_f32_e64 v34, -v36, s98
	v_exp_f32_e32 v34, v34
	v_min_f32_e64 v32, -v32, s98
	v_exp_f32_e32 v32, v32
	v_add_f32_e32 v35, 1.0, v34
	v_rcp_f32_e32 v36, v35
	v_min_f32_e64 v35, -v37, s98
	v_exp_f32_e32 v35, v35
	v_min_f32_e32 v33, 0x42a00000, v33
	v_exp_f32_e32 v33, v33
	v_add_f32_e32 v37, 1.0, v35
	v_rcp_f32_e32 v64, v37
	s_nop 0
	v_mul_f32_e32 v116, v35, v64
	v_min_f32_e64 v35, -v38, s98
	v_exp_f32_e32 v35, v35
	s_nop 0
	v_add_f32_e32 v37, 1.0, v35
	v_rcp_f32_e32 v73, v37
	s_nop 0
	v_mul_f32_e32 v76, v35, v73
	v_min_f32_e64 v35, -v39, s98
	v_exp_f32_e32 v38, v35
	s_nop 0
	v_add_f32_e32 v35, 1.0, v38
	v_rcp_f32_e32 v126, v35
	v_min_f32_e64 v35, -v40, s98
	v_exp_f32_e32 v40, v35
	v_min_f32_e64 v35, -v41, s98
	v_exp_f32_e32 v41, v35
	s_nop 0
	v_pk_add_f32 v[128:129], v[40:41], 1.0 op_sel_hi:[1,0]
	v_rcp_f32_e32 v128, v128
	v_rcp_f32_e32 v129, v129
	v_min_f32_e64 v35, -v42, s98
	v_exp_f32_e32 v42, v35
	v_min_f32_e64 v35, -v43, s98
	v_exp_f32_e32 v43, v35
	v_pk_mul_f32 v[40:41], v[40:41], v[128:129]
	v_pk_add_f32 v[130:131], v[42:43], 1.0 op_sel_hi:[1,0]
	v_rcp_f32_e32 v130, v130
	v_rcp_f32_e32 v131, v131
	v_min_f32_e64 v35, -v44, s98
	v_exp_f32_e32 v44, v35
	v_min_f32_e64 v35, -v45, s98
	v_exp_f32_e32 v132, v35
	v_min_f32_e64 v35, -v46, s98
	v_exp_f32_e32 v45, v35
	v_min_f32_e64 v35, -v47, s98
	v_exp_f32_e32 v133, v35
	v_pk_add_f32 v[46:47], v[32:33], 1.0 op_sel_hi:[1,0]
	v_rcp_f32_e32 v46, v46
	v_rcp_f32_e32 v47, v47
	v_pk_add_f32 v[134:135], v[114:115], 1.0 op_sel_hi:[1,0]
	v_rcp_f32_e32 v134, v134
	v_rcp_f32_e32 v135, v135
	v_pk_mul_f32 v[42:43], v[42:43], v[130:131]
	v_pk_mul_f32 v[32:33], v[32:33], v[46:47]
	v_pk_mul_f32 v[138:139], v[40:41], v[40:41] op_sel_hi:[0,1]
	v_pk_mul_f32 v[114:115], v[114:115], v[134:135]
	v_pk_mul_f32 v[140:141], v[42:43], v[42:43] op_sel_hi:[0,1]
	v_pk_mul_f32 v[136:137], v[32:33], v[114:115]
	v_pk_add_f32 v[142:143], v[44:45], 1.0 op_sel_hi:[1,0]
	v_rcp_f32_e32 v142, v142
	v_rcp_f32_e32 v143, v143
	v_pk_add_f32 v[144:145], v[132:133], 1.0 op_sel_hi:[1,0]
	v_rcp_f32_e32 v144, v144
	v_rcp_f32_e32 v145, v145
	v_pk_mul_f32 v[44:45], v[44:45], v[142:143]
	v_pk_mul_f32 v[132:133], v[132:133], v[144:145]
	s_nop 0
	v_pk_mul_f32 v[146:147], v[44:45], v[132:133]
	s_nop 0
	v_pk_mul_f32 v[146:147], v[146:147], v[146:147] op_sel:[0,1] op_sel_hi:[1,0]
	ds_bpermute_b32 v127, v104, v146
	s_waitcnt lgkmcnt(0)
	v_mul_f32_e32 v32, v77, v127
	v_cndmask_b32_e64 v32, v77, v32, s[14:15]
	v_mul_f32_e32 v35, v32, v133
	v_mul_f32_e32 v37, v45, v35
	v_mul_f32_e32 v39, v132, v37
	v_mul_f32_e32 v105, v143, v35
	v_mul_f32_e32 v132, v144, v37
	v_mov_b32_e32 v35, v139
	v_mov_b32_e32 v37, v141
	v_pk_mul_f32 v[34:35], v[34:35], v[36:37]
	ds_bpermute_b32 v117, v104, v35
	v_mul_f32_e32 v133, v142, v39
	v_mov_b32_e32 v39, v146
	v_pk_mul_f32 v[38:39], v[38:39], v[126:127]
	v_mul_f32_e32 v40, v32, v145
	v_pk_mul_f32 v[44:45], v[76:77], v[38:39]
	s_waitcnt lgkmcnt(0)
	v_pk_mul_f32 v[34:35], v[34:35], v[116:117]
	v_mul_f32_e32 v32, v45, v117
	v_pk_mul_f32 v[34:35], v[34:35], v[44:45]
	ds_bpermute_b32 v37, v104, v34
	v_cndmask_b32_e64 v32, v45, v32, s[14:15]
	v_mul_f32_e32 v39, v43, v32
	v_mul_f32_e32 v43, v131, v32
	v_mul_f32_e32 v42, v42, v39
	s_waitcnt lgkmcnt(0)
	v_mul_f32_e32 v32, v35, v37
	v_cndmask_b32_e64 v32, v35, v32, s[14:15]
	v_mul_f32_e32 v38, v38, v32
	v_mul_f32_e32 v44, v130, v39
	v_mul_f32_e32 v39, v76, v38
	v_mul_f32_e32 v45, v116, v39
	v_mul_f32_e32 v73, v73, v38
	v_mul_f32_e32 v64, v64, v39
	v_mul_f32_e32 v45, v36, v45
	v_mov_b32_e32 v38, v136
	v_mov_b32_e32 v39, v34
	v_mov_b32_e32 v36, v137
	v_pk_mul_f32 v[36:37], v[38:39], v[36:37]
	ds_bpermute_b32 v34, v104, v36
	v_mul_f32_e32 v76, v126, v32
	v_mul_f32_e32 v41, v41, v42
	v_mul_f32_e32 v42, v129, v42
	v_mul_f32_e32 v41, v128, v41
	s_waitcnt lgkmcnt(0)
	v_pk_mul_f32 v[36:37], v[36:37], v[34:35]
	s_nop 0
	v_mul_f32_e32 v32, v37, v34
	v_cndmask_b32_e64 v32, v37, v32, s[14:15]
	v_mul_f32_e32 v34, v115, v32
	v_mul_f32_e32 v33, v33, v34
	v_mul_f32_e32 v35, v114, v33
	v_mul_f32_e32 v38, v135, v32
	v_mul_f32_e32 v34, v47, v34
	v_mul_f32_e32 v32, v134, v33
	v_mul_f32_e32 v33, v46, v35
	v_cvt_pk_bf16_f32 v32, v33, v32
	v_cvt_pk_bf16_f32 v33, v34, v38
	v_cvt_pk_bf16_f32 v34, v45, v64
	v_cvt_pk_bf16_f32 v35, v73, v76
	v_mul_f32_e32 v77, v36, v37
	v_cmp_eq_f32_e32 vcc, 0, v77
	s_waitcnt vmcnt(2)
	v_mfma_f32_32x32x16_bf16 v[0:15], v[106:109], v[32:35], v[0:15]
	s_cmp_lg_u64 vcc, exec
	s_cselect_b64 s[86:87], -1, 0
	s_add_i32 s63, s63, -1
	s_cmp_lg_u32 s72, 0
	s_cselect_b64 s[88:89], -1, 0
	s_and_b64 s[86:87], s[88:89], s[86:87]
	s_add_i32 s72, s72, 1
	s_waitcnt vmcnt(1)
	v_mfma_f32_32x32x16_bf16 v[16:31], v[118:121], v[32:35], v[16:31]
	v_cvt_pk_bf16_f32 v32, v41, v42
	v_cvt_pk_bf16_f32 v33, v44, v43
	v_cvt_pk_bf16_f32 v34, v133, v132
	v_cvt_pk_bf16_f32 v35, v105, v40
	s_and_b64 vcc, exec, s[86:87]
	s_waitcnt vmcnt(0)
	v_mfma_f32_32x32x16_bf16 v[0:15], v[110:113], v[32:35], v[0:15]
	v_mfma_f32_32x32x16_bf16 v[16:31], v[122:125], v[32:35], v[16:31]
	s_cbranch_vccnz .LBB0_1752
	s_branch .LBB0_1743
